# grid barriers 2..13 with leader write-back and direct top-counter polling, code placement of every later loop kept identical (mod 64) to the previous version
# speedup vs baseline: 1.0042x; 1.0042x over previous
; __device__ __forceinline__ void phase_sba_attn(const Params& p, u16* sm) {
;     ...
;       bf16x8 Lh[2], Ll[2];
; #pragma unroll
;       for (int k2 = 0; k2 < 2; ++k2) {
;         uint32_t hw[4], lw[4];
; #pragma unroll
;         for (int e2 = 0; e2 < 4; ++e2) {
;           const int mt = 2 * k2 + (e2 >> 1), j = (e2 & 1) * 2;
;           hw[e2] = pack2(L[mt][j], L[mt][j + 1]);
;           const float r0 = L[mt][j] - __uint_as_float(hw[e2] << 16), r1 = L[mt][j + 1] - __uint_as_float(hw[e2] & 0xffff0000u);
;           lw[e2] = pack2(r0, r1);
;         }
;         Lh[k2] = mk_frag(hw[0], hw[1], hw[2], hw[3]);
;         Ll[k2] = mk_frag(lw[0], lw[1], lw[2], lw[3]);
;       }
;       f32x4 cum[4];
; #pragma unroll
;       for (int ms = 0; ms < 4; ++ms) {
;         const int a = ms >> 1, bb = ms & 1;
;         f32x4 c = (f32x4){0.f, 0.f, 0.f, 0.f};
;         c = mfma16(tri[bb], Lh[a], c);
;         c = mfma16(tri[bb], Ll[a], c);
;         if (a == 0) { c = mfma16(ones, Lh[1], c); c = mfma16(ones, Ll[1], c); }
;         cum[ms] = c;
;       }
;       float tot = cum[0][0] + L[0][0];
;       tot = __shfl(tot, fr);
;       bf16x8 pf[2];
; #pragma unroll
;       for (int k2 = 0; k2 < 2; ++k2) {
;         uint32_t pw[4];
; #pragma unroll
;         for (int e2 = 0; e2 < 4; ++e2) {
;           const int mt = 2 * k2 + (e2 >> 1), j = (e2 & 1) * 2;
;           float p0 = __builtin_amdgcn_exp2f(lb[mt][j] + cum[mt][j] + carry);
;           float p1 = __builtin_amdgcn_exp2f(lb[mt][j + 1] + cum[mt][j + 1] + carry);
.LBB0_335:
	s_or_b64 exec, exec, s[8:9]
	s_nop 1
	v_cvt_pk_bf16_f32 v44, v2, v3
	v_lshlrev_b32_e32 v46, 16, v44
	v_and_b32_e32 v47, 0xffff0000, v44
	v_pk_add_f32 v[46:47], v[2:3], v[46:47] neg_lo:[0,1] neg_hi:[0,1]
	v_cvt_pk_bf16_f32 v45, v116, v117
	v_cvt_pk_bf16_f32 v48, v46, v47
	v_lshlrev_b32_e32 v3, 16, v45
	v_and_b32_e32 v46, 0xffff0000, v45
	v_sub_f32_e32 v3, v116, v3
	v_sub_f32_e32 v46, v117, v46
	v_cvt_pk_bf16_f32 v49, v3, v46
	v_cvt_pk_bf16_f32 v46, v118, v119
	v_lshlrev_b32_e32 v3, 16, v46
	v_and_b32_e32 v47, 0xffff0000, v46
	v_sub_f32_e32 v3, v118, v3
	v_sub_f32_e32 v47, v119, v47
	v_cvt_pk_bf16_f32 v50, v3, v47
	v_cvt_pk_bf16_f32 v47, v120, v121
	v_lshlrev_b32_e32 v3, 16, v47
	v_and_b32_e32 v51, 0xffff0000, v47
	v_sub_f32_e32 v3, v120, v3
	v_sub_f32_e32 v51, v121, v51
	v_cvt_pk_bf16_f32 v52, v123, v124
	v_cvt_pk_bf16_f32 v51, v3, v51
	v_lshlrev_b32_e32 v3, 16, v52
	v_and_b32_e32 v53, 0xffff0000, v52
	v_sub_f32_e32 v3, v123, v3
	v_sub_f32_e32 v53, v124, v53
	v_cvt_pk_bf16_f32 v56, v3, v53
	v_cvt_pk_bf16_f32 v53, v125, v126
	v_lshlrev_b32_e32 v3, 16, v53
	v_and_b32_e32 v54, 0xffff0000, v53
	v_sub_f32_e32 v3, v125, v3
	v_sub_f32_e32 v54, v126, v54
	v_cvt_pk_bf16_f32 v57, v3, v54
	v_cvt_pk_bf16_f32 v54, v127, v128
	v_mfma_f32_16x16x32_bf16 v[116:119], v[8:11], v[44:47], 0
	v_lshlrev_b32_e32 v3, 16, v54
	s_mov_b32 s18, s16
	s_mov_b32 s19, s16
	v_sub_f32_e32 v3, v127, v3
	s_mov_b32 s17, s16
	v_mov_b64_e32 v[126:127], s[18:19]
	v_mov_b64_e32 v[124:125], s[16:17]
	v_mfma_f32_16x16x32_bf16 v[116:119], v[8:11], v[48:51], v[116:119]
	v_and_b32_e32 v55, 0xffff0000, v54
	v_sub_f32_e32 v55, v128, v55
	v_cvt_pk_bf16_f32 v58, v3, v55
	v_mfma_f32_16x16x32_bf16 v[44:47], v[4:7], v[44:47], 0
	v_cvt_pk_bf16_f32 v55, v130, v129
	v_lshlrev_b32_e32 v3, 16, v55
	v_and_b32_e32 v59, 0xffff0000, v55
	v_mfma_f32_16x16x32_bf16 v[116:119], v[124:127], v[52:55], v[116:119]
	v_sub_f32_e32 v3, v130, v3
	v_sub_f32_e32 v59, v129, v59
	v_cvt_pk_bf16_f32 v59, v3, v59
	v_mfma_f32_16x16x32_bf16 v[44:47], v[4:7], v[48:51], v[44:47]
	s_nop 0
	v_mfma_f32_16x16x32_bf16 v[116:119], v[124:127], v[56:59], v[116:119]
	v_mfma_f32_16x16x32_bf16 v[44:47], v[124:127], v[52:55], v[44:47]
	v_mfma_f32_16x16x32_bf16 v[48:51], v[8:11], v[52:55], 0
	s_nop 5
	v_add_f32_e32 v3, v78, v116
	v_add_f32_e32 v3, v0, v3
	v_exp_f32_e32 v3, v3
	v_mfma_f32_16x16x32_bf16 v[52:55], v[4:7], v[52:55], 0
	v_add_f32_e32 v2, v2, v116
	ds_bpermute_b32 v2, v112, v2
	v_mfma_f32_16x16x32_bf16 v[44:47], v[124:127], v[56:59], v[44:47]
	v_mfma_f32_16x16x32_bf16 v[48:51], v[8:11], v[56:59], v[48:51]
	v_mfma_f32_16x16x32_bf16 v[52:55], v[4:7], v[56:59], v[52:55]
	v_add_f32_e32 v56, v79, v117
	v_add_f32_e32 v56, v0, v56
	v_exp_f32_e32 v56, v56
	s_andn2_b64 s[8:9], exec, vcc
	s_cbranch_scc0 .Lsba_um
; __device__ __forceinline__ void phase_sba_attn(const Params& p, u16* sm) {
;     ...
;       bf16x8 pf[2];
; #pragma unroll
;       for (int k2 = 0; k2 < 2; ++k2) {
;         uint32_t pw[4];
; #pragma unroll
;         for (int e2 = 0; e2 < 4; ++e2) {
;           const int mt = 2 * k2 + (e2 >> 1), j = (e2 & 1) * 2;
;           float p0 = __builtin_amdgcn_exp2f(lb[mt][j] + cum[mt][j] + carry);
;           float p1 = __builtin_amdgcn_exp2f(lb[mt][j + 1] + cum[mt][j + 1] + carry);
;           if (tile_masked) {
;             p0 = ((vmask >> (mt * 4 + j)) & 1u) ? p0 : 0.f;
;             p1 = ((vmask >> (mt * 4 + j + 1)) & 1u) ? p1 : 0.f;
;           }
;           pw[e2] = pack2(p0, p1);
;         }
;         pf[k2] = mk_frag(pw[0], pw[1], pw[2], pw[3]);
;       }
; #pragma unroll
;       for (int k2 = 0; k2 < 2; ++k2)
; #pragma unroll
;         for (int dm = 0; dm < 4; ++dm) {
;           bf16x8 vf = *(const bf16x8*)(sV + (dm * 16 + fr) * LDSP + k2 * 32 + fq * 8);
;           o[dm] = mfma16(vf, pf[k2], o[dm]);
;         }
;       carry += tot;
	v_and_b32_e32 v57, 1, v122
	v_cmp_eq_u32_e64 s[8:9], 1, v57
	v_and_b32_e32 v57, 2, v122
	v_cmp_ne_u32_e64 s[10:11], 0, v57
	s_or_b64 s[8:9], vcc, s[8:9]
	v_cndmask_b32_e64 v3, 0, v3, s[8:9]
	s_or_b64 s[8:9], vcc, s[10:11]
	v_cndmask_b32_e64 v56, 0, v56, s[8:9]
	v_cvt_pk_bf16_f32 v56, v3, v56
	v_add_f32_e32 v3, v80, v118
	v_add_f32_e32 v3, v0, v3
	v_add_f32_e32 v57, v81, v119
	v_exp_f32_e32 v3, v3
	v_add_f32_e32 v57, v0, v57
	v_exp_f32_e32 v57, v57
	v_and_b32_e32 v58, 4, v122
	v_cmp_ne_u32_e64 s[8:9], 0, v58
	v_and_b32_e32 v58, 8, v122
	v_cmp_ne_u32_e64 s[10:11], 0, v58
	s_or_b64 s[8:9], vcc, s[8:9]
	v_cndmask_b32_e64 v3, 0, v3, s[8:9]
	s_or_b64 s[8:9], vcc, s[10:11]
	v_cndmask_b32_e64 v57, 0, v57, s[8:9]
	v_cvt_pk_bf16_f32 v57, v3, v57
	v_add_f32_e32 v3, v82, v44
	v_add_f32_e32 v3, v0, v3
	v_add_f32_e32 v44, v83, v45
	v_exp_f32_e32 v3, v3
	v_add_f32_e32 v44, v0, v44
	v_exp_f32_e32 v44, v44
	v_and_b32_e32 v45, 16, v122
	v_cmp_ne_u32_e64 s[8:9], 0, v45
	v_and_b32_e32 v45, 32, v122
	v_cmp_ne_u32_e64 s[10:11], 0, v45
	s_or_b64 s[8:9], vcc, s[8:9]
	v_cndmask_b32_e64 v3, 0, v3, s[8:9]
	s_or_b64 s[8:9], vcc, s[10:11]
	v_cndmask_b32_e64 v44, 0, v44, s[8:9]
	v_cvt_pk_bf16_f32 v58, v3, v44
	v_add_f32_e32 v3, v84, v46
	v_add_f32_e32 v3, v0, v3
	v_add_f32_e32 v44, v85, v47
	v_exp_f32_e32 v3, v3
	v_add_f32_e32 v44, v0, v44
	v_exp_f32_e32 v44, v44
	v_and_b32_e32 v45, 64, v122
	v_cmp_ne_u32_e64 s[8:9], 0, v45
	v_and_b32_e32 v45, 0x80, v122
	v_cmp_ne_u32_e64 s[10:11], 0, v45
	s_or_b64 s[8:9], vcc, s[8:9]
	v_cndmask_b32_e64 v3, 0, v3, s[8:9]
	s_or_b64 s[8:9], vcc, s[10:11]
	v_cndmask_b32_e64 v44, 0, v44, s[8:9]
	v_cvt_pk_bf16_f32 v59, v3, v44
	v_add_f32_e32 v3, v86, v48
	v_add_f32_e32 v3, v0, v3
	v_add_f32_e32 v44, v87, v49
	v_exp_f32_e32 v3, v3
	v_add_f32_e32 v44, v0, v44
	v_exp_f32_e32 v44, v44
	v_and_b32_e32 v45, 0x100, v122
	v_cmp_ne_u32_e64 s[8:9], 0, v45
	v_and_b32_e32 v45, 0x200, v122
	v_cmp_ne_u32_e64 s[10:11], 0, v45
	s_or_b64 s[8:9], vcc, s[8:9]
	v_cndmask_b32_e64 v3, 0, v3, s[8:9]
	s_or_b64 s[8:9], vcc, s[10:11]
	v_cndmask_b32_e64 v44, 0, v44, s[8:9]
	v_cvt_pk_bf16_f32 v44, v3, v44
	v_add_f32_e32 v3, v88, v50
	v_add_f32_e32 v3, v0, v3
	v_add_f32_e32 v45, v89, v51
	v_exp_f32_e32 v3, v3
	v_add_f32_e32 v45, v0, v45
	v_exp_f32_e32 v45, v45
	v_and_b32_e32 v46, 0x400, v122
	v_cmp_ne_u32_e64 s[8:9], 0, v46
	v_and_b32_e32 v46, 0x800, v122
	v_cmp_ne_u32_e64 s[10:11], 0, v46
	s_or_b64 s[8:9], vcc, s[8:9]
	v_cndmask_b32_e64 v3, 0, v3, s[8:9]
	s_or_b64 s[8:9], vcc, s[10:11]
	v_cndmask_b32_e64 v45, 0, v45, s[8:9]
	v_cvt_pk_bf16_f32 v45, v3, v45
	v_add_f32_e32 v3, v90, v52
	v_add_f32_e32 v3, v0, v3
	v_add_f32_e32 v46, v91, v53
	v_exp_f32_e32 v3, v3
	v_add_f32_e32 v46, v0, v46
	v_exp_f32_e32 v46, v46
	v_and_b32_e32 v47, 0x1000, v122
	v_cmp_ne_u32_e64 s[8:9], 0, v47
	v_and_b32_e32 v47, 0x2000, v122
	v_cmp_ne_u32_e64 s[10:11], 0, v47
	s_or_b64 s[8:9], vcc, s[8:9]
	v_cndmask_b32_e64 v3, 0, v3, s[8:9]
	s_or_b64 s[8:9], vcc, s[10:11]
	v_cndmask_b32_e64 v46, 0, v46, s[8:9]
	v_cvt_pk_bf16_f32 v46, v3, v46
	v_add_f32_e32 v3, v92, v54
	ds_read_b128 v[48:51], v115 offset:9216
	v_add_f32_e32 v47, v93, v55
	ds_read_b128 v[52:55], v115 offset:11520
	ds_read_b128 v[78:81], v115 offset:13824
	ds_read_b128 v[82:85], v115 offset:9280
	v_and_b32_e32 v86, 0x4000, v122
	s_waitcnt lgkmcnt(2)
	v_mfma_f32_16x16x32_bf16 v[36:39], v[52:55], v[56:59], v[36:39]
	v_and_b32_e32 v52, 0x8000, v122
	v_cmp_ne_u32_e64 s[8:9], 0, v86
	v_cmp_ne_u32_e64 s[10:11], 0, v52
	v_mfma_f32_16x16x32_bf16 v[40:43], v[48:51], v[56:59], v[40:43]
	ds_read_b128 v[48:51], v115 offset:16128
	ds_read_b128 v[86:89], v115 offset:11584
	ds_read_b128 v[52:55], v115 offset:13888
	v_add_f32_e32 v3, v0, v3
	s_waitcnt lgkmcnt(4)
	v_mfma_f32_16x16x32_bf16 v[24:27], v[78:81], v[56:59], v[24:27]
	ds_read_b128 v[78:81], v115 offset:16192
	v_add_f32_e32 v47, v0, v47
	v_exp_f32_e32 v3, v3
	v_exp_f32_e32 v47, v47
	s_waitcnt lgkmcnt(3)
	v_mfma_f32_16x16x32_bf16 v[20:23], v[48:51], v[56:59], v[20:23]
	s_or_b64 s[8:9], vcc, s[8:9]
	s_or_b64 vcc, vcc, s[10:11]
	v_cndmask_b32_e64 v3, 0, v3, s[8:9]
	v_cndmask_b32_e32 v47, 0, v47, vcc
	v_cvt_pk_bf16_f32 v47, v3, v47
	v_add_f32_e32 v0, v0, v2
	s_nop 0
	v_mfma_f32_16x16x32_bf16 v[40:43], v[82:85], v[44:47], v[40:43]
	s_waitcnt lgkmcnt(2)
	v_mfma_f32_16x16x32_bf16 v[36:39], v[86:89], v[44:47], v[36:39]
	s_waitcnt lgkmcnt(1)
	v_mfma_f32_16x16x32_bf16 v[24:27], v[52:55], v[44:47], v[24:27]
	s_waitcnt lgkmcnt(0)
	v_mfma_f32_16x16x32_bf16 v[20:23], v[78:81], v[44:47], v[20:23]
	s_branch .LBB0_336
	s_nop 0
	s_nop 0
.Lsba_um:
	v_cvt_pk_bf16_f32 v56, v3, v56
	v_add_f32_e32 v3, v80, v118
	v_add_f32_e32 v3, v0, v3
	v_add_f32_e32 v57, v81, v119
	v_exp_f32_e32 v3, v3
	v_add_f32_e32 v57, v0, v57
	v_exp_f32_e32 v57, v57
	s_nop 0
	v_cvt_pk_bf16_f32 v57, v3, v57
	v_add_f32_e32 v3, v82, v44
	v_add_f32_e32 v3, v0, v3
	v_add_f32_e32 v44, v83, v45
	v_exp_f32_e32 v3, v3
	v_add_f32_e32 v44, v0, v44
	v_exp_f32_e32 v44, v44
	s_nop 0
	v_cvt_pk_bf16_f32 v58, v3, v44
	v_add_f32_e32 v3, v84, v46
	v_add_f32_e32 v3, v0, v3
	v_add_f32_e32 v44, v85, v47
	v_exp_f32_e32 v3, v3
	v_add_f32_e32 v44, v0, v44
	v_exp_f32_e32 v44, v44
	s_nop 0
	v_cvt_pk_bf16_f32 v59, v3, v44
	v_add_f32_e32 v3, v86, v48
	v_add_f32_e32 v3, v0, v3
	v_add_f32_e32 v44, v87, v49
	v_exp_f32_e32 v3, v3
	v_add_f32_e32 v44, v0, v44
	v_exp_f32_e32 v44, v44
	s_nop 0
	v_cvt_pk_bf16_f32 v44, v3, v44
	v_add_f32_e32 v3, v88, v50
	v_add_f32_e32 v3, v0, v3
	v_add_f32_e32 v45, v89, v51
	v_exp_f32_e32 v3, v3
	v_add_f32_e32 v45, v0, v45
	v_exp_f32_e32 v45, v45
	s_nop 0
	v_cvt_pk_bf16_f32 v45, v3, v45
	v_add_f32_e32 v3, v90, v52
	v_add_f32_e32 v3, v0, v3
	v_add_f32_e32 v46, v91, v53
	v_exp_f32_e32 v3, v3
	v_add_f32_e32 v46, v0, v46
	v_exp_f32_e32 v46, v46
	s_nop 0
	v_cvt_pk_bf16_f32 v46, v3, v46
	v_add_f32_e32 v3, v92, v54
	ds_read_b128 v[48:51], v115 offset:9216
	v_add_f32_e32 v47, v93, v55
	ds_read_b128 v[52:55], v115 offset:11520
	ds_read_b128 v[78:81], v115 offset:13824
	ds_read_b128 v[82:85], v115 offset:9280
	s_waitcnt lgkmcnt(2)
	v_mfma_f32_16x16x32_bf16 v[36:39], v[52:55], v[56:59], v[36:39]
	v_mfma_f32_16x16x32_bf16 v[40:43], v[48:51], v[56:59], v[40:43]
	ds_read_b128 v[48:51], v115 offset:16128
	ds_read_b128 v[86:89], v115 offset:11584
	ds_read_b128 v[52:55], v115 offset:13888
	v_add_f32_e32 v3, v0, v3
	s_waitcnt lgkmcnt(4)
	v_mfma_f32_16x16x32_bf16 v[24:27], v[78:81], v[56:59], v[24:27]
	ds_read_b128 v[78:81], v115 offset:16192
	v_add_f32_e32 v47, v0, v47
	v_exp_f32_e32 v3, v3
	v_exp_f32_e32 v47, v47
	s_waitcnt lgkmcnt(3)
	v_mfma_f32_16x16x32_bf16 v[20:23], v[48:51], v[56:59], v[20:23]
	v_cvt_pk_bf16_f32 v47, v3, v47
	v_add_f32_e32 v0, v0, v2
	s_nop 0
	v_mfma_f32_16x16x32_bf16 v[40:43], v[82:85], v[44:47], v[40:43]
	s_waitcnt lgkmcnt(2)
	v_mfma_f32_16x16x32_bf16 v[36:39], v[86:89], v[44:47], v[36:39]
	s_waitcnt lgkmcnt(1)
	v_mfma_f32_16x16x32_bf16 v[24:27], v[52:55], v[44:47], v[24:27]
	s_waitcnt lgkmcnt(0)
	v_mfma_f32_16x16x32_bf16 v[20:23], v[78:81], v[44:47], v[20:23]

; #define LAS __attribute__((address_space(3)))
; __device__ __forceinline__ unsigned xb_ld(unsigned* p)              { return __hip_atomic_load(p, __ATOMIC_RELAXED, __HIP_MEMORY_SCOPE_AGENT); }
; __device__ __forceinline__ unsigned xb_add(unsigned* p, unsigned v) { return __hip_atomic_fetch_add(p, v, __ATOMIC_RELAXED, __HIP_MEMORY_SCOPE_AGENT); }
; #define XB_SPIN(cond) do { unsigned _sp = 0; while (cond) { __builtin_amdgcn_s_sleep(1); if (++_sp > (1u << 24)) break; } } while (0)
; __device__ __forceinline__ void grid_barrier(unsigned* bar, volatile LAS unsigned* st, unsigned k) {
;   asm volatile("s_waitcnt vmcnt(0)" ::: "memory");
;   __syncthreads();
;   if (threadIdx.x == 0) {
;     __builtin_amdgcn_s_waitcnt(0);
;     const unsigned nloc = st[0], nx = st[1], x = st[2];
;     const unsigned old = xb_add(&bar[XB_XSUB(x)], 1u);
;     if (old + 1u == (k + 1u) * nloc) {
;       __builtin_amdgcn_fence(__ATOMIC_RELEASE, "agent");
;       asm volatile("s_waitcnt vmcnt(0)" ::: "memory");
;       const unsigned og = xb_add(&bar[XB_TOP], 1u);
;       if (og + 1u == (k + 1u) * nx) xb_add(&bar[XB_TOPGEN], 1u);
;       else XB_SPIN(xb_ld(&bar[XB_TOPGEN]) == k);
;       __builtin_amdgcn_fence(__ATOMIC_ACQUIRE, "agent");
;       xb_add(&bar[XB_XGEN(x)], 1u);
;       asm volatile("s_waitcnt vmcnt(0)" ::: "memory");
;     } else {
;       XB_SPIN(xb_ld(&bar[XB_XGEN(x)]) == k);
;       __builtin_amdgcn_fence(__ATOMIC_ACQUIRE, "agent");
;       asm volatile("s_waitcnt vmcnt(0)" ::: "memory");
;     }
;   }
;   __syncthreads();
.Llb2_spin:
	global_load_dword v1, v0, s[6:7] sc1
	s_add_u32 vcc_lo, vcc_lo, 1
	s_waitcnt vmcnt(0)
	v_readfirstlane_b32 s8, v1
	s_cmp_ge_u32 vcc_lo, 0x400000
	s_cbranch_scc1 .Llb2_done
	s_cmp_ge_u32 s8, s10
	s_cbranch_scc1 .Llb2_done
	s_sleep 1
	s_branch .Llb2_spin
	s_nop 0
	s_nop 0
	s_nop 0
	s_nop 0
	s_nop 0
	s_nop 0
	s_nop 0
	s_nop 0

; #define LAS __attribute__((address_space(3)))
; __device__ __forceinline__ unsigned xb_ld(unsigned* p)              { return __hip_atomic_load(p, __ATOMIC_RELAXED, __HIP_MEMORY_SCOPE_AGENT); }
; __device__ __forceinline__ unsigned xb_add(unsigned* p, unsigned v) { return __hip_atomic_fetch_add(p, v, __ATOMIC_RELAXED, __HIP_MEMORY_SCOPE_AGENT); }
; #define XB_SPIN(cond) do { unsigned _sp = 0; while (cond) { __builtin_amdgcn_s_sleep(1); if (++_sp > (1u << 24)) break; } } while (0)
; __device__ __forceinline__ void grid_barrier(unsigned* bar, volatile LAS unsigned* st, unsigned k) {
;   asm volatile("s_waitcnt vmcnt(0)" ::: "memory");
;   __syncthreads();
;   if (threadIdx.x == 0) {
;     __builtin_amdgcn_s_waitcnt(0);
;     const unsigned nloc = st[0], nx = st[1], x = st[2];
;     const unsigned old = xb_add(&bar[XB_XSUB(x)], 1u);
;     if (old + 1u == (k + 1u) * nloc) {
;       __builtin_amdgcn_fence(__ATOMIC_RELEASE, "agent");
;       asm volatile("s_waitcnt vmcnt(0)" ::: "memory");
;       const unsigned og = xb_add(&bar[XB_TOP], 1u);
;       if (og + 1u == (k + 1u) * nx) xb_add(&bar[XB_TOPGEN], 1u);
;       else XB_SPIN(xb_ld(&bar[XB_TOPGEN]) == k);
;       __builtin_amdgcn_fence(__ATOMIC_ACQUIRE, "agent");
;       xb_add(&bar[XB_XGEN(x)], 1u);
;       asm volatile("s_waitcnt vmcnt(0)" ::: "memory");
;     } else {
;       XB_SPIN(xb_ld(&bar[XB_XGEN(x)]) == k);
;       __builtin_amdgcn_fence(__ATOMIC_ACQUIRE, "agent");
;       asm volatile("s_waitcnt vmcnt(0)" ::: "memory");
;     }
;   }
;   __syncthreads();
.Llb4_spin:
	global_load_dword v1, v0, s[6:7] sc1
	s_add_u32 vcc_lo, vcc_lo, 1
	s_waitcnt vmcnt(0)
	v_readfirstlane_b32 s8, v1
	s_cmp_ge_u32 vcc_lo, 0x400000
	s_cbranch_scc1 .Llb4_done
	s_cmp_ge_u32 s8, s10
	s_cbranch_scc1 .Llb4_done
	s_sleep 1
	s_branch .Llb4_spin
	s_nop 0
	s_nop 0
	s_nop 0
	s_nop 0
	s_nop 0
	s_nop 0
	s_nop 0
